# k=10 OpResid epilogue pipelined like k=7 (gate quads once, 5 row groups of x in flight, saddr addressing)
# baseline (speedup 1.0000x reference)
;     __device__ __forceinline__ void operator()(int row, int col, f32x4 v0, f32x4 v1) const { *(u32x4*)(G + (size_t)row * 1024 + col) = pack8(v0, v1); }
;     __device__ __forceinline__ void operator()(const pg8::f32x4 (&acc)[2][2][4][2], const pg8::Unit& u, int wr, int wc, int fr, int fq) const {
;     ...
;         for (int ai = 0; ai < 2; ++ai)
; #pragma unroll
;             for (int m = 0; m < 4; ++m)
; #pragma unroll
;                 for (int bj = 0; bj < 2; ++bj) { op(row0 + ai * 128 + m * 16, col0 + bj * 128, acc[ai][bj][m][0], acc[ai][bj][m][1]); asm volatile("" ::: "memory"); }
;     __device__ __forceinline__ void operator()(int row, int col, f32x4 v0, f32x4 v1) const {
;         const float* xi; float* xo; const float* g;
;         if (row < ML) { xi = xl + (size_t)row * 1024 + col; xo = ol + (size_t)row * 1024 + col; g = mod + (size_t)(row >> 11) * 6144 + gi * 1024 + col; }
;         else { const size_t rr = (size_t)(row - ML) * 1024 + col; xi = xc + rr; xo = oc + rr; g = mod + (size_t)8 * 6144 + gi * 1024 + col; }
;         const f32x4 x0 = *(const f32x4*)xi, x1 = *(const f32x4*)(xi + 4), g0 = *(const f32x4*)g, g1 = *(const f32x4*)(g + 4);
;         *(f32x4*)xo = x0 + g0 * v0; *(f32x4*)(xo + 4) = x1 + g1 * v1;
;     }
.LBB0_751:
	s_waitcnt lgkmcnt(0)
	s_lshl_b32 s6, s97, 8
	s_add_i32 s6, s6, s39
	s_lshl_b32 s7, s96, 10
	v_lshlrev_b32_e32 v170, 12, v154
	v_lshlrev_b32_e32 v171, 2, v156
	s_cmpk_gt_i32 s6, 0x3fff
	s_cbranch_scc1 .Lk10_ctx
	s_mov_b64 s[4:5], s[48:49]
	s_ashr_i32 s60, s6, 11
	s_mul_i32 s60, s60, 0x6000
	s_branch .Lk10_addr
.Lk10_ctx:
	s_mov_b64 s[4:5], s[84:85]
	s_addk_i32 s6, 0xc000
	s_mov_b32 s60, 0x30000
.Lk10_addr:
	v_add_u32_e32 v170, v170, v171
	s_lshl_b32 s6, s6, 12
	s_add_u32 s6, s6, s7
	s_add_u32 s60, s60, s7
	s_add_u32 s98, s56, s60
	s_addc_u32 s99, s57, 0
	s_add_u32 s4, s4, s6
	s_addc_u32 s5, s5, 0
	s_mov_b64 s[96:97], s[4:5]
	global_load_dwordx4 v[142:145], v171, s[98:99]
	global_load_dwordx4 v[146:149], v171, s[98:99] offset:16
	global_load_dwordx4 v[150:153], v171, s[98:99] offset:512
	global_load_dwordx4 v[158:161], v171, s[98:99] offset:528
	global_load_dwordx4 v[198:201], v170, s[4:5]
	global_load_dwordx4 v[202:205], v170, s[4:5] offset:16
	global_load_dwordx4 v[206:209], v170, s[4:5] offset:512
	global_load_dwordx4 v[210:213], v170, s[4:5] offset:528
	s_add_u32 s4, s4, 0x10000
	s_addc_u32 s5, s5, 0
	global_load_dwordx4 v[214:217], v170, s[4:5]
	global_load_dwordx4 v[218:221], v170, s[4:5] offset:16
	global_load_dwordx4 v[222:225], v170, s[4:5] offset:512
	global_load_dwordx4 v[226:229], v170, s[4:5] offset:528
	s_add_u32 s4, s4, 0x10000
	s_addc_u32 s5, s5, 0
	global_load_dwordx4 v[162:165], v170, s[4:5]
	global_load_dwordx4 v[166:169], v170, s[4:5] offset:16
	s_waitcnt vmcnt(8)
	v_pk_fma_f32 v[126:127], v[126:127], v[142:143], v[198:199]
	v_pk_fma_f32 v[128:129], v[128:129], v[144:145], v[200:201]
	v_pk_fma_f32 v[122:123], v[122:123], v[146:147], v[202:203]
	v_pk_fma_f32 v[124:125], v[124:125], v[148:149], v[204:205]
	global_store_dwordx4 v170, v[126:129], s[96:97]
	global_store_dwordx4 v170, v[122:125], s[96:97] offset:16
	global_load_dwordx4 v[198:201], v170, s[4:5] offset:512
	global_load_dwordx4 v[202:205], v170, s[4:5] offset:528
	s_waitcnt vmcnt(10)
	v_pk_fma_f32 v[118:119], v[118:119], v[150:151], v[206:207]
	v_pk_fma_f32 v[120:121], v[120:121], v[152:153], v[208:209]
	v_pk_fma_f32 v[114:115], v[114:115], v[158:159], v[210:211]
	v_pk_fma_f32 v[116:117], v[116:117], v[160:161], v[212:213]
	global_store_dwordx4 v170, v[118:121], s[96:97] offset:512
	global_store_dwordx4 v170, v[114:117], s[96:97] offset:528
	s_add_u32 s4, s4, 0x10000
	s_addc_u32 s5, s5, 0
	global_load_dwordx4 v[206:209], v170, s[4:5]
	global_load_dwordx4 v[210:213], v170, s[4:5] offset:16
	s_waitcnt vmcnt(12)
	v_pk_fma_f32 v[110:111], v[110:111], v[142:143], v[214:215]
	v_pk_fma_f32 v[112:113], v[112:113], v[144:145], v[216:217]
	v_pk_fma_f32 v[106:107], v[106:107], v[146:147], v[218:219]
	v_pk_fma_f32 v[108:109], v[108:109], v[148:149], v[220:221]
	s_add_u32 s96, s96, 0x10000
	s_addc_u32 s97, s97, 0
	global_store_dwordx4 v170, v[110:113], s[96:97]
	global_store_dwordx4 v170, v[106:109], s[96:97] offset:16
	global_load_dwordx4 v[214:217], v170, s[4:5] offset:512
	global_load_dwordx4 v[218:221], v170, s[4:5] offset:528
	s_waitcnt vmcnt(14)
	v_pk_fma_f32 v[102:103], v[102:103], v[150:151], v[222:223]
	v_pk_fma_f32 v[104:105], v[104:105], v[152:153], v[224:225]
	v_pk_fma_f32 v[98:99], v[98:99], v[158:159], v[226:227]
	v_pk_fma_f32 v[100:101], v[100:101], v[160:161], v[228:229]
	global_store_dwordx4 v170, v[102:105], s[96:97] offset:512
	global_store_dwordx4 v170, v[98:101], s[96:97] offset:528
	s_add_u32 s4, s4, 0x50000
	s_addc_u32 s5, s5, 0
	global_load_dwordx4 v[222:225], v170, s[4:5]
	global_load_dwordx4 v[226:229], v170, s[4:5] offset:16
	s_waitcnt vmcnt(16)
	v_pk_fma_f32 v[94:95], v[94:95], v[142:143], v[162:163]
	v_pk_fma_f32 v[96:97], v[96:97], v[144:145], v[164:165]
	v_pk_fma_f32 v[90:91], v[90:91], v[146:147], v[166:167]
	v_pk_fma_f32 v[92:93], v[92:93], v[148:149], v[168:169]
	s_add_u32 s96, s96, 0x10000
	s_addc_u32 s97, s97, 0
	global_store_dwordx4 v170, v[94:97], s[96:97]
	global_store_dwordx4 v170, v[90:93], s[96:97] offset:16
	global_load_dwordx4 v[162:165], v170, s[4:5] offset:512
	global_load_dwordx4 v[166:169], v170, s[4:5] offset:528
	s_waitcnt vmcnt(16)
	v_pk_fma_f32 v[86:87], v[86:87], v[150:151], v[198:199]
	v_pk_fma_f32 v[88:89], v[88:89], v[152:153], v[200:201]
	v_pk_fma_f32 v[82:83], v[82:83], v[158:159], v[202:203]
	v_pk_fma_f32 v[84:85], v[84:85], v[160:161], v[204:205]
	global_store_dwordx4 v170, v[86:89], s[96:97] offset:512
	global_store_dwordx4 v170, v[82:85], s[96:97] offset:528
	s_add_u32 s4, s4, 0x10000
	s_addc_u32 s5, s5, 0
	global_load_dwordx4 v[198:201], v170, s[4:5]
	global_load_dwordx4 v[202:205], v170, s[4:5] offset:16
	s_waitcnt vmcnt(16)
;     __device__ __forceinline__ void operator()(int row, int col, f32x4 v0, f32x4 v1) const { *(u32x4*)(G + (size_t)row * 1024 + col) = pack8(v0, v1); }
;     __device__ __forceinline__ void operator()(const pg8::f32x4 (&acc)[2][2][4][2], const pg8::Unit& u, int wr, int wc, int fr, int fq) const {
;     ...
;         for (int ai = 0; ai < 2; ++ai)
; #pragma unroll
;             for (int m = 0; m < 4; ++m)
; #pragma unroll
;                 for (int bj = 0; bj < 2; ++bj) { op(row0 + ai * 128 + m * 16, col0 + bj * 128, acc[ai][bj][m][0], acc[ai][bj][m][1]); asm volatile("" ::: "memory"); }
;     __device__ __forceinline__ void operator()(int row, int col, f32x4 v0, f32x4 v1) const {
;         const float* xi; float* xo; const float* g;
;         if (row < ML) { xi = xl + (size_t)row * 1024 + col; xo = ol + (size_t)row * 1024 + col; g = mod + (size_t)(row >> 11) * 6144 + gi * 1024 + col; }
;         else { const size_t rr = (size_t)(row - ML) * 1024 + col; xi = xc + rr; xo = oc + rr; g = mod + (size_t)8 * 6144 + gi * 1024 + col; }
;         const f32x4 x0 = *(const f32x4*)xi, x1 = *(const f32x4*)(xi + 4), g0 = *(const f32x4*)g, g1 = *(const f32x4*)(g + 4);
;         *(f32x4*)xo = x0 + g0 * v0; *(f32x4*)(xo + 4) = x1 + g1 * v1;
;     }
	v_pk_fma_f32 v[78:79], v[78:79], v[142:143], v[206:207]
	v_pk_fma_f32 v[80:81], v[80:81], v[144:145], v[208:209]
	v_pk_fma_f32 v[74:75], v[74:75], v[146:147], v[210:211]
	v_pk_fma_f32 v[76:77], v[76:77], v[148:149], v[212:213]
	s_add_u32 s96, s96, 0x10000
	s_addc_u32 s97, s97, 0
	global_store_dwordx4 v170, v[78:81], s[96:97]
	global_store_dwordx4 v170, v[74:77], s[96:97] offset:16
	global_load_dwordx4 v[206:209], v170, s[4:5] offset:512
	global_load_dwordx4 v[210:213], v170, s[4:5] offset:528
	s_waitcnt vmcnt(16)
	v_pk_fma_f32 v[70:71], v[70:71], v[150:151], v[214:215]
	v_pk_fma_f32 v[72:73], v[72:73], v[152:153], v[216:217]
	v_pk_fma_f32 v[66:67], v[66:67], v[158:159], v[218:219]
	v_pk_fma_f32 v[68:69], v[68:69], v[160:161], v[220:221]
	global_store_dwordx4 v170, v[70:73], s[96:97] offset:512
	global_store_dwordx4 v170, v[66:69], s[96:97] offset:528
	s_add_u32 s4, s4, 0x10000
	s_addc_u32 s5, s5, 0
	global_load_dwordx4 v[214:217], v170, s[4:5]
	global_load_dwordx4 v[218:221], v170, s[4:5] offset:16
	s_waitcnt vmcnt(16)
	v_pk_fma_f32 v[62:63], v[62:63], v[142:143], v[222:223]
	v_pk_fma_f32 v[64:65], v[64:65], v[144:145], v[224:225]
	v_pk_fma_f32 v[58:59], v[58:59], v[146:147], v[226:227]
	v_pk_fma_f32 v[60:61], v[60:61], v[148:149], v[228:229]
	s_add_u32 s96, s96, 0x50000
	s_addc_u32 s97, s97, 0
	global_store_dwordx4 v170, v[62:65], s[96:97]
	global_store_dwordx4 v170, v[58:61], s[96:97] offset:16
	global_load_dwordx4 v[222:225], v170, s[4:5] offset:512
	global_load_dwordx4 v[226:229], v170, s[4:5] offset:528
	s_waitcnt vmcnt(16)
	v_pk_fma_f32 v[54:55], v[54:55], v[150:151], v[162:163]
	v_pk_fma_f32 v[56:57], v[56:57], v[152:153], v[164:165]
	v_pk_fma_f32 v[50:51], v[50:51], v[158:159], v[166:167]
	v_pk_fma_f32 v[52:53], v[52:53], v[160:161], v[168:169]
	global_store_dwordx4 v170, v[54:57], s[96:97] offset:512
	global_store_dwordx4 v170, v[50:53], s[96:97] offset:528
	s_add_u32 s4, s4, 0x10000
	s_addc_u32 s5, s5, 0
	global_load_dwordx4 v[162:165], v170, s[4:5]
	global_load_dwordx4 v[166:169], v170, s[4:5] offset:16
	s_waitcnt vmcnt(16)
	v_pk_fma_f32 v[46:47], v[46:47], v[142:143], v[198:199]
	v_pk_fma_f32 v[48:49], v[48:49], v[144:145], v[200:201]
	v_pk_fma_f32 v[42:43], v[42:43], v[146:147], v[202:203]
	v_pk_fma_f32 v[44:45], v[44:45], v[148:149], v[204:205]
	s_add_u32 s96, s96, 0x10000
	s_addc_u32 s97, s97, 0
	global_store_dwordx4 v170, v[46:49], s[96:97]
	global_store_dwordx4 v170, v[42:45], s[96:97] offset:16
	global_load_dwordx4 v[198:201], v170, s[4:5] offset:512
	global_load_dwordx4 v[202:205], v170, s[4:5] offset:528
	s_waitcnt vmcnt(16)
	v_pk_fma_f32 v[38:39], v[38:39], v[150:151], v[206:207]
	v_pk_fma_f32 v[40:41], v[40:41], v[152:153], v[208:209]
	v_pk_fma_f32 v[34:35], v[34:35], v[158:159], v[210:211]
	v_pk_fma_f32 v[36:37], v[36:37], v[160:161], v[212:213]
	global_store_dwordx4 v170, v[38:41], s[96:97] offset:512
	global_store_dwordx4 v170, v[34:37], s[96:97] offset:528
	s_waitcnt vmcnt(14)
	v_pk_fma_f32 v[30:31], v[30:31], v[142:143], v[214:215]
	v_pk_fma_f32 v[32:33], v[32:33], v[144:145], v[216:217]
	v_pk_fma_f32 v[26:27], v[26:27], v[146:147], v[218:219]
	v_pk_fma_f32 v[28:29], v[28:29], v[148:149], v[220:221]
	s_add_u32 s96, s96, 0x10000
	s_addc_u32 s97, s97, 0
	global_store_dwordx4 v170, v[30:33], s[96:97]
	global_store_dwordx4 v170, v[26:29], s[96:97] offset:16
	s_waitcnt vmcnt(12)
	v_pk_fma_f32 v[22:23], v[22:23], v[150:151], v[222:223]
	v_pk_fma_f32 v[24:25], v[24:25], v[152:153], v[224:225]
	v_pk_fma_f32 v[18:19], v[18:19], v[158:159], v[226:227]
	v_pk_fma_f32 v[20:21], v[20:21], v[160:161], v[228:229]
	global_store_dwordx4 v170, v[22:25], s[96:97] offset:512
	global_store_dwordx4 v170, v[18:21], s[96:97] offset:528
	s_waitcnt vmcnt(10)
	v_pk_fma_f32 v[14:15], v[14:15], v[142:143], v[162:163]
	v_pk_fma_f32 v[16:17], v[16:17], v[144:145], v[164:165]
	v_pk_fma_f32 v[10:11], v[10:11], v[146:147], v[166:167]
	v_pk_fma_f32 v[12:13], v[12:13], v[148:149], v[168:169]
	s_add_u32 s96, s96, 0x10000
	s_addc_u32 s97, s97, 0
	global_store_dwordx4 v170, v[14:17], s[96:97]
	global_store_dwordx4 v170, v[10:13], s[96:97] offset:16
	s_waitcnt vmcnt(8)
	v_pk_fma_f32 v[6:7], v[6:7], v[150:151], v[198:199]
	v_pk_fma_f32 v[8:9], v[8:9], v[152:153], v[200:201]
	v_pk_fma_f32 v[2:3], v[2:3], v[158:159], v[202:203]
	v_pk_fma_f32 v[4:5], v[4:5], v[160:161], v[204:205]
	global_store_dwordx4 v170, v[6:9], s[96:97] offset:512
	global_store_dwordx4 v170, v[2:5], s[96:97] offset:528
	s_and_b64 vcc, exec, s[40:41]
	s_mov_b64 s[4:5], -1
	s_cbranch_vccnz .LBB0_739
	s_andn2_b64 vcc, exec, s[50:51]
	s_cbranch_vccnz .LBB0_738
	s_barrier
	s_branch .LBB0_738
